# adds P3 layer1 third round moved after the grid barrier (overlaps gate-up phase), flag wait before sample-row gate-up units
# speedup vs baseline: 1.0089x; 1.0089x over previous
;     __device__ __forceinline__ bool next(int i, Unit& u) const {
;         constexpr int NU = (33792 / BM) * NN;
;         const int L = i * G + ((NU - i * G < G) ? vp : v); if (L >= NU) return false;
;         constexpr int NM = 33792 / BM, NFULL = (NM / 8) * 8 * NN;
;         if (L < NFULL) { const int g = L / (8 * NN), idx = L % (8 * NN); u.pm = g * 8 + (idx & 7); u.pn = idx >> 3; }
;         else { constexpr int GS = NM % 8 ? NM % 8 : 8; const int idx = L - NFULL; u.pm = (NM / 8) * 8 + idx % GS; u.pn = idx / GS; }
;         return true;
;     }
; template <int KK, class Epi, class Sched, bool ALIGN_EPI = true>
; __device__ __forceinline__ void gemm_phase(LAS unsigned char* lds, const bf16* gA, const bf16* gBt, const Sched& S, const Epi& E, const int wid) {
;     ...
;     Unit cur, nxt; int ui = 0;
;     if (!S.next(0, cur)) return;
.LBB0_1165:
	s_or_b64 exec, exec, s[6:7]
	s_mov_b32 s76, 0
	s_barrier
.Lp3b_entry:
	s_and_b64 vcc, exec, s[74:75]
	s_mov_b32 s0, s86
	s_cbranch_vccz .LBB0_1170
	s_and_b64 vcc, exec, s[74:75]
	s_mov_b32 s1, s0
	s_cbranch_vccz .LBB0_1171
.LBB0_1167:
	v_readlane_b32 s2, v249, 17
	v_readlane_b32 s3, v249, 18
	s_and_b64 s[2:3], s[2:3], exec
	s_cselect_b32 s2, s1, s0
	s_cmp_eq_u32 s76, 1
	s_cbranch_scc0 .Lp3b_f0
	s_add_i32 s2, s86, 0x110
.Lp3b_f0:
	s_cmpk_lt_i32 s2, 0x210
	v_mov_b32_e32 v0, v196
	s_cselect_b64 s[6:7], -1, 0
	s_cmpk_gt_i32 s2, 0x20f
	s_cbranch_scc1 .LBB0_1174
	s_cmpk_gt_i32 s2, 0x1ff
	s_cbranch_scc0 .LBB0_1172
	s_add_i32 s3, s2, 0xfffffe00
	s_and_b32 s4, s2, 3
	s_or_b32 s38, s4, 0x80
	s_lshr_b32 s36, s3, 2
	s_cbranch_execz .LBB0_1173
	s_branch .LBB0_1174

;     __device__ __forceinline__ bool next(int i, Unit& u) const {
;         constexpr int NU = (33792 / BM) * NN;
;         const int L = i * G + ((NU - i * G < G) ? vp : v); if (L >= NU) return false;
;         constexpr int NM = 33792 / BM, NFULL = (NM / 8) * 8 * NN;
;         if (L < NFULL) { const int g = L / (8 * NN), idx = L % (8 * NN); u.pm = g * 8 + (idx & 7); u.pn = idx >> 3; }
;         else { constexpr int GS = NM % 8 ? NM % 8 : 8; const int idx = L - NFULL; u.pm = (NM / 8) * 8 + idx % GS; u.pn = idx / GS; }
;         return true;
;     }
; template <int KK, class Epi, class Sched, bool ALIGN_EPI = true>
; __device__ __forceinline__ void gemm_phase(LAS unsigned char* lds, const bf16* gA, const bf16* gBt, const Sched& S, const Epi& E, const int wid) {
;     ...
;         const bool has_next = S.next(ui + 1, nxt);
;         const char* nA = has_next ? (const char*)gA + (size_t)nxt.pm * tstep : cA; const char* nB = has_next ? (const char*)gBt + (size_t)nxt.pn * tstep : cB;
.LBB0_1180:
	s_add_i32 s48, s48, 1
	s_mul_i32 s15, s48, s64
	s_sub_i32 s17, 0x210, s15
	s_cmp_lt_i32 s17, s64
	s_cselect_b32 s17, s1, s0
	s_add_i32 s15, s17, s15
	s_cmp_lg_u32 s64, 0x100
	s_cbranch_scc1 .Lp3b_s
	s_cmp_eq_u32 s76, 1
	s_cbranch_scc1 .Lp3b_none
	s_cmpk_lt_i32 s15, 0x200
	s_cbranch_scc1 .Lp3b_s
.Lp3b_none:
	s_movk_i32 s15, 0x210
.Lp3b_s:
	s_cmpk_lt_i32 s15, 0x210
	s_cselect_b64 s[24:25], -1, 0
	s_cmpk_gt_i32 s15, 0x20f
	s_cbranch_scc1 .LBB0_1185
	s_cmpk_gt_i32 s15, 0x1ff
	s_mov_b64 s[26:27], -1
	s_cbranch_scc0 .LBB0_1183
	s_add_i32 s16, s15, 0xfffffe00
	s_and_b32 s14, s15, 3
	s_bitset1_b32 s14, 7
	s_lshr_b32 s16, s16, 2
	s_mov_b64 s[26:27], 0

; __device__ __forceinline__ void grid_bar(unsigned* bar, unsigned k, unsigned G, unsigned bid, bool leader) {
;     asm volatile("s_waitcnt vmcnt(0) lgkmcnt(0)" ::: "memory");
;     __syncthreads();
;     if (leader) {
.LBB0_1209:
	s_cmp_eq_u32 s76, 1
	s_cbranch_scc1 .Lp3b_done2
	v_readlane_b32 s0, v249, 54
	v_readlane_b32 s1, v249, 55
	s_and_b64 vcc, exec, s[0:1]
	s_mov_b64 s[8:9], 0
	s_cbranch_vccnz .LBB0_1211
	v_mov_b32_e32 v0, v196
	s_nop 0
	v_cmp_eq_u32_e32 vcc, 0, v0
	s_and_b64 s[8:9], vcc, exec

; __device__ __forceinline__ void grid_bar(unsigned* bar, unsigned k, unsigned G, unsigned bid, bool leader) {
;     ...
;         __builtin_amdgcn_fence(__ATOMIC_ACQUIRE, "agent");
;         asm volatile("s_waitcnt vmcnt(0)" ::: "memory");
;     }
;     __syncthreads();
; }
.LBB0_1226:
	s_or_b64 exec, exec, s[6:7]
	s_barrier
	s_cmp_lg_u32 s64, 0x100
	s_cbranch_scc1 .Lp3b_after
	s_cmp_lg_u32 s76, 0
	s_cbranch_scc1 .Lp3b_after
	s_cmp_lt_u32 s86, 0xf0
	s_cbranch_scc1 .Lp3b_after
	s_mov_b32 s76, 1
	s_branch .Lp3b_entry
.Lp3b_done2:
	s_waitcnt vmcnt(0) lgkmcnt(0)
	v_readlane_b32 s77, v249, 0
	s_nop 3
	s_cmp_lg_u32 s77, 0
	s_cbranch_scc1 .Lp3b_rel_done
	buffer_wbl2 sc1
	s_waitcnt vmcnt(0)
	v_mov_b32_e32 v2, 0
	v_mov_b32_e32 v3, 1
	s_mov_b64 s[78:79], exec
	s_mov_b64 exec, 1
	global_atomic_add v2, v3, s[20:21] offset:3456
	s_waitcnt vmcnt(0)
	s_mov_b64 exec, s[78:79]
.Lp3b_rel_done:
	s_mov_b32 s76, 2

;     __device__ __forceinline__ bool next(int i, Unit& u) const {
;         constexpr int NU = (33792 / BM) * NN;
;         const int L = i * G + ((NU - i * G < G) ? vp : v); if (L >= NU) return false;
;         constexpr int NM = 33792 / BM, NFULL = (NM / 8) * 8 * NN;
;         if (L < NFULL) { const int g = L / (8 * NN), idx = L % (8 * NN); u.pm = g * 8 + (idx & 7); u.pn = idx >> 3; }
;         else { constexpr int GS = NM % 8 ? NM % 8 : 8; const int idx = L - NFULL; u.pm = (NM / 8) * 8 + idx % GS; u.pn = idx / GS; }
;         return true;
;     }
; template <int KK, class Epi, class Sched, bool ALIGN_EPI = true>
; __device__ __forceinline__ void gemm_phase(LAS unsigned char* lds, const bf16* gA, const bf16* gBt, const Sched& S, const Epi& E, const int wid) {
;     ...
;         const bool has_next = S.next(ui + 1, nxt);
;         const char* nA = has_next ? (const char*)gA + (size_t)nxt.pm * tstep : cA; const char* nB = has_next ? (const char*)gBt + (size_t)nxt.pn * tstep : cB;
.LBB0_1240:
	s_add_i32 s48, s48, 1
	s_mul_i32 s15, s48, s64
	s_sub_i32 s17, 0xb58, s15
	s_cmp_lt_i32 s17, s64
	s_cselect_b32 s17, s1, s0
	s_add_i32 s15, s17, s15
	s_cmpk_lt_i32 s15, 0xb58
	s_cselect_b64 s[24:25], -1, 0
	s_cmpk_gt_i32 s15, 0xb57
	s_cbranch_scc1 .LBB0_1245
	s_cmpk_gt_i32 s15, 0xaff
	s_mov_b64 s[26:27], -1
	s_cbranch_scc0 .LBB0_1243
	s_cmp_lg_u32 s64, 0x100
	s_cbranch_scc1 .Lp4b_ok
	v_mov_b32_e32 v0, 0
.Lp4b_poll:
	global_load_dword v1, v0, s[20:21] offset:3456 sc1
	s_waitcnt vmcnt(0)
	v_readfirstlane_b32 s77, v1
	s_nop 0
	s_cmp_ge_u32 s77, 16
	s_cbranch_scc1 .Lp4b_ok
	s_sleep 2
	s_branch .Lp4b_poll
.Lp4b_ok:
	buffer_inv sc1
	s_waitcnt vmcnt(0)
	s_add_i32 s16, s15, 0xfffff500
	s_and_b32 s14, s15, 3
	s_bitset1_b32 s14, 7
	s_lshr_b32 s16, s16, 2
	s_mov_b64 s[26:27], 0
